# scan loader waves run at s_setprio 1
# baseline (speedup 1.0000x reference)
.LBB0_497:
	s_and_saveexec_b64 s[0:1], s[80:81]
	s_xor_b64 s[84:85], exec, s[0:1]
	s_cbranch_execz .LBB0_652
	s_setprio 1
	s_lshl_b32 s0, s53, 4
	s_and_b32 s0, s0, 0x70
	s_ashr_i32 s38, s53, 4
	s_add_i32 s0, s0, s38
	s_lshl_b32 s54, s0, 6
	s_and_b32 s86, s54, 0xfffff800
	s_and_b32 s1, s0, 31
	s_ashr_i32 s87, s86, 31
	s_lshl_b32 s39, s1, 6
	s_lshl_b32 s82, s1, 8
	s_lshl_b64 s[4:5], s[86:87], 11
	v_lshl_add_u64 v[2:3], v[120:121], 0, s[82:83]
	s_or_b32 s0, s4, s39
	global_load_dwordx4 v[36:39], v[2:3], off
	v_lshl_add_u64 v[2:3], v[122:123], 0, s[82:83]
	v_mov_b32_e32 v77, s5
	v_or_b32_e32 v76, s0, v94
	global_load_dwordx4 v[40:43], v[2:3], off
	v_lshl_add_u64 v[2:3], v[124:125], 0, s[82:83]
	v_lshl_add_u64 v[48:49], v[76:77], 0, v[96:97]
	global_load_dwordx4 v[44:47], v[2:3], off
	v_lshlrev_b64 v[2:3], 1, v[48:49]
	v_lshl_add_u64 v[50:51], s[68:69], 0, v[2:3]
	v_lshl_add_u64 v[2:3], s[70:71], 0, v[2:3]
	global_load_dwordx2 v[68:69], v[50:51], off
	global_load_dwordx2 v[70:71], v[2:3], off
	s_bfe_u32 s41, s53, 0x10003
	v_readfirstlane_b32 s0, v95
	v_cmp_eq_u32_e64 s[30:31], s41, v109
	v_mov_b32_e32 v74, 0
	v_mov_b32_e32 v56, 0
	v_mov_b32_e32 v57, 0
	s_and_saveexec_b64 s[4:5], s[30:31]
	s_cbranch_execz .LBB0_500
	v_lshl_add_u64 v[50:51], v[48:49], 1, s[72:73]
	global_load_dwordx2 v[56:57], v[50:51], off

.LBB0_652:
	s_setprio 0
	s_andn2_saveexec_b64 s[4:5], s[84:85]
	s_cbranch_execz .LBB0_496
	v_mbcnt_lo_u32_b32 v1, -1, 0
	v_mbcnt_hi_u32_b32 v1, -1, v1
	v_mov_b32_e32 v36, 0
	v_mov_b32_e32 v37, 0
	v_mov_b32_e32 v38, 0
	v_mov_b32_e32 v39, 0
	v_lshlrev_b32_e32 v1, 4, v1
	v_add_u32_e32 v1, 0x22000, v1
	s_waitcnt vmcnt(0)
	ds_write_b128 v1, v[36:39]
	s_mov_b32 s6, 0xaaaaaaaa
	s_mov_b32 s7, 0xaaaaaaaa
	s_mov_b32 s10, 0xcccccccc
	s_mov_b32 s11, 0xcccccccc
	v_cmp_eq_u32_e64 s[18:19], 0, v196
	v_mov_b32_e32 v34, 0x17080
	v_add_u32_e32 v35, 0xc200, v207
	v_mov_b64_e32 v[2:3], 0
	v_mov_b64_e32 v[4:5], 0
	v_mov_b64_e32 v[6:7], 0
	v_mov_b64_e32 v[8:9], 0
	v_mov_b32_e32 v14, 0
	s_mov_b32 s0, 0
	s_waitcnt lgkmcnt(0)
	s_barrier
